# virtual block id permuted: phase 3/4 tile loops put one busy workgroup per CU first (first resident slot of each XCD)
# speedup vs baseline: 1.0240x; 1.0058x over previous
.LBB0_17:
	s_or_b64 exec, exec, s[2:3]
	s_load_dwordx16 s[4:19], s[0:1], 0x0
	s_and_b32 s2, s90, 7
	s_cmp_lg_u32 s2, 0
	s_waitcnt lgkmcnt(0)
	v_writelane_b32 v251, s4, 8
	s_nop 1
	v_writelane_b32 v251, s5, 9
	v_writelane_b32 v251, s6, 10
	v_writelane_b32 v251, s7, 11
	v_writelane_b32 v251, s8, 12
	v_writelane_b32 v251, s9, 13
	v_writelane_b32 v251, s10, 14
	v_writelane_b32 v251, s11, 15
	v_writelane_b32 v251, s12, 16
	v_writelane_b32 v251, s13, 17
	v_writelane_b32 v251, s14, 18
	v_writelane_b32 v251, s15, 19
	v_writelane_b32 v251, s16, 20
	v_writelane_b32 v251, s17, 21
	v_writelane_b32 v251, s18, 22
	v_writelane_b32 v251, s19, 23
	v_writelane_b32 v251, s33, 24
	s_cbranch_scc1 .LBB0_19
	s_and_b32 s2, s33, 7
	s_ashr_i32 s3, s90, 3
	s_mul_i32 s2, s3, s2
	s_lshr_b32 s3, s33, 3
	s_add_i32 s2, s2, s3
	v_writelane_b32 v251, s2, 24
	s_cmpk_lg_i32 s90, 0x200
	s_cbranch_scc1 .LBB0_19
	s_and_b32 s2, s33, 7
	s_lshl_b32 s2, s2, 5
	s_add_i32 s2, s2, s3
	s_lshr_b32 s3, s3, 5
	s_mul_i32 s3, s3, 0xe0
	s_add_i32 s2, s2, s3
	s_nop 0
	v_writelane_b32 v251, s2, 24
